# attention epilogue: attn_out_g vectors loaded once early instead of 16 serialized loads
# speedup vs baseline: 1.0025x; 1.0025x over previous
; __device__ __forceinline__ unsigned cvt_pk_bf16(float lo, float hi) { const cvt_f32x2_t v = {lo, hi}; const cvt_bf16x2_t b = __builtin_convertvector(v, cvt_bf16x2_t); return __builtin_bit_cast(unsigned, b); }
; __device__ __forceinline__ float rsq(float x) { return __builtin_amdgcn_rsqf(x); }
; __device__ __forceinline__ void attn_phase(LAS unsigned char* lds, const bf16_t* Qb, const bf16_t* Kb, const bf16_t* VT, bf16_t* MIX,
;                                            const float* tblg, const float* ga) {
;     ...
;         for (int qt = 0; qt < 4; ++qt) {
;             float tot = 0.f;
; #pragma unroll
;             for (int w = 0; w < 8; ++w) tot += red[w * 64 + 16 * qt + fr];
;             const float rs = rsq(tot * (1.0f / AW) + EPS);
;             bf16_t* op = MIX + (size_t)(b * SEQ + r * 64 + 16 * qt + fr) * DM + h * 64 + 4 * fq;
; #pragma unroll
;             for (int nt = 0; nt < 4; ++nt) { const f32x4 g4 = *(const f32x4*)(ga + h * 64 + 16 * nt + 4 * fq); const f32x4 a = O[qt][nt] * rs * g4;
;                 u32x2 w; w.x = cvt_pk_bf16(a[0], a[1]); w.y = cvt_pk_bf16(a[2], a[3]); *(u32x2*)(op + 16 * nt) = w; }
;         }
.LBB0_647:
	s_or_b64 exec, exec, s[6:7]
	s_waitcnt lgkmcnt(0)
	s_barrier
	v_add_u32_e32 v84, 0xf000, v189
	ds_read2_b32 v[46:47], v84 offset1:16
	ds_read2_b32 v[48:49], v84 offset0:64 offset1:80
	ds_read2_b32 v[50:51], v84 offset0:128 offset1:144
	ds_read2_b32 v[60:61], v84 offset0:192 offset1:208
	s_lshl_b32 s6, s16, 11
	s_waitcnt lgkmcnt(3)
	v_add_f32_e32 v45, 0, v46
	s_waitcnt lgkmcnt(2)
	v_add_f32_e32 v45, v45, v48
	s_waitcnt lgkmcnt(1)
	v_add_f32_e32 v45, v45, v50
	s_waitcnt lgkmcnt(0)
	v_add_f32_e32 v45, v45, v60
	v_add_u32_e32 v60, 0xf400, v189
	ds_read2_b32 v[62:63], v60 offset1:16
	ds_read2_b32 v[68:69], v60 offset0:64 offset1:80
	ds_read2_b32 v[70:71], v60 offset0:128 offset1:144
	ds_read2_b32 v[72:73], v60 offset0:192 offset1:208
	s_lshl_b32 s7, s17, 6
	s_waitcnt lgkmcnt(3)
	v_add_f32_e32 v45, v45, v62
	s_waitcnt lgkmcnt(2)
	v_add_f32_e32 v45, v45, v68
	s_waitcnt lgkmcnt(1)
	v_add_f32_e32 v45, v45, v70
	s_waitcnt lgkmcnt(0)
	v_add_f32_e32 v45, v45, v72
	v_fmamk_f32 v45, v45, 0x3b000000, v241
	v_rsq_f32_e32 v46, v45
	s_add_i32 s6, s6, s7
	v_or_b32_e32 v44, s6, v188
	v_ashrrev_i32_e32 v45, 31, v44
	v_pk_mul_f32 v[80:81], v[100:101], v[46:47] op_sel_hi:[1,0]
	v_pk_mul_f32 v[82:83], v[102:103], v[46:47] op_sel_hi:[1,0]
	v_lshlrev_b64 v[74:75], 11, v[44:45]
	v_lshl_add_u64 v[74:75], v[170:171], 0, v[74:75]
	v_pk_mul_f32 v[64:65], v[64:65], v[46:47] op_sel_hi:[1,0]
	v_pk_mul_f32 v[66:67], v[66:67], v[46:47] op_sel_hi:[1,0]
	v_pk_mul_f32 v[56:57], v[56:57], v[46:47] op_sel_hi:[1,0]
	v_pk_mul_f32 v[58:59], v[58:59], v[46:47] op_sel_hi:[1,0]
	v_add_f32_e32 v45, 0, v47
	v_add_f32_e32 v45, v45, v49
	v_add_f32_e32 v45, v45, v51
	v_add_f32_e32 v45, v45, v61
	v_add_f32_e32 v45, v45, v63
	v_add_f32_e32 v45, v45, v69
	v_add_f32_e32 v45, v45, v71
	v_add_f32_e32 v45, v45, v73
	v_fmamk_f32 v45, v45, 0x3b000000, v241
	v_rsq_f32_e32 v50, v45
	s_add_i32 s9, s9, s85
	s_add_i32 s8, s8, 1
	s_cmpk_gt_i32 s9, 0x3ff
	v_pk_mul_f32 v[32:33], v[32:33], v[50:51] op_sel_hi:[1,0]
	v_pk_mul_f32 v[34:35], v[34:35], v[50:51] op_sel_hi:[1,0]
	v_pk_mul_f32 v[36:37], v[36:37], v[50:51] op_sel_hi:[1,0]
	v_pk_mul_f32 v[38:39], v[38:39], v[50:51] op_sel_hi:[1,0]
	s_waitcnt vmcnt(0)
	v_pk_mul_f32 v[78:79], v[114:115], v[80:81]
	v_pk_mul_f32 v[76:77], v[112:113], v[82:83]
	s_nop 0
	v_cvt_pk_bf16_f32 v76, v76, v77
	v_cvt_pk_bf16_f32 v77, v78, v79
	global_store_dwordx2 v[74:75], v[76:77], off
	v_pk_mul_f32 v[64:65], v[118:119], v[64:65]
	v_pk_mul_f32 v[66:67], v[116:117], v[66:67]
	v_pk_mul_f32 v[76:77], v[104:105], v[46:47] op_sel_hi:[1,0]
	v_cvt_pk_bf16_f32 v66, v66, v67
	v_cvt_pk_bf16_f32 v67, v64, v65
	global_store_dwordx2 v[74:75], v[66:67], off offset:32
	v_pk_mul_f32 v[78:79], v[106:107], v[46:47] op_sel_hi:[1,0]
	v_or_b32_e32 v46, 16, v44
	v_ashrrev_i32_e32 v47, 31, v46
	v_lshlrev_b64 v[46:47], 11, v[46:47]
	v_pk_mul_f32 v[66:67], v[122:123], v[76:77]
	v_pk_mul_f32 v[64:65], v[120:121], v[78:79]
	s_nop 0
	v_cvt_pk_bf16_f32 v64, v64, v65
	v_cvt_pk_bf16_f32 v65, v66, v67
	global_store_dwordx2 v[74:75], v[64:65], off offset:64
	v_pk_mul_f32 v[56:57], v[126:127], v[56:57]
	v_pk_mul_f32 v[58:59], v[124:125], v[58:59]
	s_nop 0
	v_cvt_pk_bf16_f32 v58, v58, v59
	v_cvt_pk_bf16_f32 v59, v56, v57
	global_store_dwordx2 v[74:75], v[58:59], off offset:96
	v_lshl_add_u64 v[56:57], v[170:171], 0, v[46:47]
	v_pk_mul_f32 v[32:33], v[114:115], v[32:33]
	v_pk_mul_f32 v[34:35], v[112:113], v[34:35]
	v_or_b32_e32 v46, 32, v44
	v_cvt_pk_bf16_f32 v34, v34, v35
	v_cvt_pk_bf16_f32 v35, v32, v33
	global_store_dwordx2 v[56:57], v[34:35], off
	v_ashrrev_i32_e32 v47, 31, v46
	v_lshlrev_b64 v[46:47], 11, v[46:47]
	v_pk_mul_f32 v[34:35], v[118:119], v[36:37]
	v_pk_mul_f32 v[32:33], v[116:117], v[38:39]
	v_pk_mul_f32 v[36:37], v[40:41], v[50:51] op_sel_hi:[1,0]
	v_cvt_pk_bf16_f32 v32, v32, v33
	v_cvt_pk_bf16_f32 v33, v34, v35
	global_store_dwordx2 v[56:57], v[32:33], off offset:32
	v_pk_mul_f32 v[38:39], v[54:55], v[50:51] op_sel_hi:[1,0]
	v_lshl_add_u64 v[54:55], v[170:171], 0, v[46:47]
	ds_read2_b32 v[40:41], v60 offset0:32 offset1:48
	v_pk_mul_f32 v[34:35], v[122:123], v[36:37]
	v_pk_mul_f32 v[32:33], v[120:121], v[38:39]
	v_pk_mul_f32 v[36:37], v[42:43], v[50:51] op_sel_hi:[1,0]
	v_cvt_pk_bf16_f32 v32, v32, v33
	v_cvt_pk_bf16_f32 v33, v34, v35
	global_store_dwordx2 v[56:57], v[32:33], off offset:64
	v_pk_mul_f32 v[38:39], v[52:53], v[50:51] op_sel_hi:[1,0]
	ds_read2_b32 v[42:43], v60 offset0:96 offset1:112
	ds_read2_b32 v[50:51], v60 offset0:160 offset1:176
	ds_read2_b32 v[52:53], v60 offset0:224 offset1:240
	v_pk_mul_f32 v[34:35], v[126:127], v[36:37]
	v_pk_mul_f32 v[32:33], v[124:125], v[38:39]
	ds_read2_b32 v[36:37], v84 offset0:160 offset1:176
	v_cvt_pk_bf16_f32 v32, v32, v33
	v_cvt_pk_bf16_f32 v33, v34, v35
	global_store_dwordx2 v[56:57], v[32:33], off offset:96
	ds_read2_b32 v[32:33], v84 offset0:32 offset1:48
	ds_read2_b32 v[34:35], v84 offset0:96 offset1:112
	ds_read2_b32 v[38:39], v84 offset0:224 offset1:240
	s_waitcnt lgkmcnt(2)
; __device__ __forceinline__ unsigned cvt_pk_bf16(float lo, float hi) { const cvt_f32x2_t v = {lo, hi}; const cvt_bf16x2_t b = __builtin_convertvector(v, cvt_bf16x2_t); return __builtin_bit_cast(unsigned, b); }
; __device__ __forceinline__ float rsq(float x) { return __builtin_amdgcn_rsqf(x); }
; __device__ __forceinline__ void attn_phase(LAS unsigned char* lds, const bf16_t* Qb, const bf16_t* Kb, const bf16_t* VT, bf16_t* MIX,
;                                            const float* tblg, const float* ga) {
;     ...
;         for (int qt = 0; qt < 4; ++qt) {
;             float tot = 0.f;
; #pragma unroll
;             for (int w = 0; w < 8; ++w) tot += red[w * 64 + 16 * qt + fr];
;             const float rs = rsq(tot * (1.0f / AW) + EPS);
;             bf16_t* op = MIX + (size_t)(b * SEQ + r * 64 + 16 * qt + fr) * DM + h * 64 + 4 * fq;
; #pragma unroll
;             for (int nt = 0; nt < 4; ++nt) { const f32x4 g4 = *(const f32x4*)(ga + h * 64 + 16 * nt + 4 * fq); const f32x4 a = O[qt][nt] * rs * g4;
;                 u32x2 w; w.x = cvt_pk_bf16(a[0], a[1]); w.y = cvt_pk_bf16(a[2], a[3]); *(u32x2*)(op + 16 * nt) = w; }
;         }
;         __syncthreads();
	v_add_f32_e32 v32, 0, v32
	s_waitcnt lgkmcnt(1)
	v_add_f32_e32 v32, v32, v34
	v_add_f32_e32 v32, v32, v36
	s_waitcnt lgkmcnt(0)
	v_add_f32_e32 v32, v32, v38
	v_add_f32_e32 v32, v32, v40
	v_add_f32_e32 v32, v32, v42
	v_add_f32_e32 v32, v32, v50
	v_add_f32_e32 v32, v32, v52
	v_fmamk_f32 v32, v32, 0x3b000000, v241
	v_rsq_f32_e32 v32, v32
	s_nop 0
	v_pk_mul_f32 v[16:17], v[16:17], v[32:33] op_sel_hi:[1,0]
	v_pk_mul_f32 v[18:19], v[18:19], v[32:33] op_sel_hi:[1,0]
	v_pk_mul_f32 v[20:21], v[20:21], v[32:33] op_sel_hi:[1,0]
	v_pk_mul_f32 v[22:23], v[22:23], v[32:33] op_sel_hi:[1,0]
	v_pk_mul_f32 v[16:17], v[114:115], v[16:17]
	v_pk_mul_f32 v[18:19], v[112:113], v[18:19]
	s_nop 0
	v_cvt_pk_bf16_f32 v18, v18, v19
	v_cvt_pk_bf16_f32 v19, v16, v17
	global_store_dwordx2 v[54:55], v[18:19], off
	v_pk_mul_f32 v[18:19], v[118:119], v[20:21]
	v_pk_mul_f32 v[16:17], v[116:117], v[22:23]
	v_pk_mul_f32 v[20:21], v[24:25], v[32:33] op_sel_hi:[1,0]
	v_cvt_pk_bf16_f32 v16, v16, v17
	v_cvt_pk_bf16_f32 v17, v18, v19
	global_store_dwordx2 v[54:55], v[16:17], off offset:32
	v_pk_mul_f32 v[22:23], v[30:31], v[32:33] op_sel_hi:[1,0]
	v_pk_mul_f32 v[18:19], v[122:123], v[20:21]
	v_pk_mul_f32 v[16:17], v[120:121], v[22:23]
	v_pk_mul_f32 v[20:21], v[26:27], v[32:33] op_sel_hi:[1,0]
	v_cvt_pk_bf16_f32 v16, v16, v17
	v_cvt_pk_bf16_f32 v17, v18, v19
	global_store_dwordx2 v[54:55], v[16:17], off offset:64
	v_pk_mul_f32 v[22:23], v[28:29], v[32:33] op_sel_hi:[1,0]
	v_pk_mul_f32 v[18:19], v[126:127], v[20:21]
	v_pk_mul_f32 v[16:17], v[124:125], v[22:23]
	s_nop 0
	v_cvt_pk_bf16_f32 v16, v16, v17
	v_cvt_pk_bf16_f32 v17, v18, v19
	global_store_dwordx2 v[54:55], v[16:17], off offset:96
	v_add_f32_e32 v16, 0, v33
	v_add_f32_e32 v16, v16, v35
	v_add_f32_e32 v16, v16, v37
	v_add_f32_e32 v16, v16, v39
	v_add_f32_e32 v16, v16, v41
	v_add_f32_e32 v16, v16, v43
	v_add_f32_e32 v16, v16, v51
	v_add_f32_e32 v16, v16, v53
	v_fmamk_f32 v16, v16, 0x3b000000, v241
	v_rsq_f32_e32 v20, v16
	v_or_b32_e32 v16, 48, v44
	v_ashrrev_i32_e32 v17, 31, v16
	v_lshlrev_b64 v[16:17], 11, v[16:17]
	v_lshl_add_u64 v[22:23], v[170:171], 0, v[16:17]
	v_pk_mul_f32 v[8:9], v[8:9], v[20:21] op_sel_hi:[1,0]
	v_pk_mul_f32 v[10:11], v[10:11], v[20:21] op_sel_hi:[1,0]
	v_pk_mul_f32 v[12:13], v[12:13], v[20:21] op_sel_hi:[1,0]
	v_pk_mul_f32 v[14:15], v[14:15], v[20:21] op_sel_hi:[1,0]
	v_pk_mul_f32 v[6:7], v[6:7], v[20:21] op_sel_hi:[1,0]
	v_pk_mul_f32 v[4:5], v[4:5], v[20:21] op_sel_hi:[1,0]
	v_pk_mul_f32 v[2:3], v[2:3], v[20:21] op_sel_hi:[1,0]
	v_pk_mul_f32 v[0:1], v[0:1], v[20:21] op_sel_hi:[1,0]
	v_pk_mul_f32 v[8:9], v[114:115], v[8:9]
	v_pk_mul_f32 v[10:11], v[112:113], v[10:11]
	s_nop 0
	v_cvt_pk_bf16_f32 v10, v10, v11
	v_cvt_pk_bf16_f32 v11, v8, v9
	global_store_dwordx2 v[22:23], v[10:11], off
	v_pk_mul_f32 v[10:11], v[118:119], v[12:13]
	v_pk_mul_f32 v[8:9], v[116:117], v[14:15]
	s_nop 0
	v_cvt_pk_bf16_f32 v8, v8, v9
	v_cvt_pk_bf16_f32 v9, v10, v11
	global_store_dwordx2 v[22:23], v[8:9], off offset:32
	v_pk_mul_f32 v[6:7], v[122:123], v[6:7]
	v_pk_mul_f32 v[4:5], v[120:121], v[4:5]
	s_nop 0
	v_cvt_pk_bf16_f32 v4, v4, v5
	v_cvt_pk_bf16_f32 v5, v6, v7
	global_store_dwordx2 v[22:23], v[4:5], off offset:64
	v_pk_mul_f32 v[2:3], v[126:127], v[2:3]
	v_pk_mul_f32 v[0:1], v[124:125], v[0:1]
	s_nop 0
	v_cvt_pk_bf16_f32 v0, v0, v1
	v_cvt_pk_bf16_f32 v1, v2, v3
	global_store_dwordx2 v[22:23], v[0:1], off offset:96
	s_barrier
	s_cbranch_scc1 .LBB0_658

; #define LAS __attribute__((address_space(3)))
; __device__ __forceinline__ void attn_phase(LAS unsigned char* lds, const bf16_t* Qb, const bf16_t* Kb, const bf16_t* VT, bf16_t* MIX,
;                                            const float* tblg, const float* ga) {
;     ...
;         ATT_LOADH(kA, vA, 0, 0);
; #pragma unroll 1
;         for (int j = 0; j < 8; ++j) {
;             const int dr = r0 + j - r + 7;
;             const LAS float* trow = tbl + (h * 15 + dr) * 128;
;             ATT_LOADH(kB, vB, j, 1);
;             ATT_HALF(kA, vA, 0);
;             { const int jn = j < 7 ? j + 1 : 7; ATT_LOADH(kA, vA, jn, 0); }
;             ATT_HALF(kB, vB, 1);
.LBB0_649:
	global_load_dwordx4 v[148:151], v[160:161], off
	global_load_dwordx4 v[152:155], v[160:161], off offset:1024
	global_load_dwordx4 v[156:159], v[160:161], off offset:2048
	s_nop 0
	global_load_dwordx4 v[160:163], v[160:161], off offset:3072
	s_nop 0
	global_load_dwordx4 v[218:221], v[186:187], off
	global_load_dwordx4 v[222:225], v[186:187], off offset:1024
	global_load_dwordx4 v[226:229], v[186:187], off offset:2048
	global_load_dwordx4 v[230:233], v[186:187], off offset:3072
	v_lshl_add_u64 v[100:101], v[184:185], 0, s[6:7]
	global_load_dwordx4 v[120:123], v[100:101], off offset:-2048
	global_load_dwordx4 v[116:119], v[100:101], off offset:-1024
	global_load_dwordx4 v[128:131], v[100:101], off
	global_load_dwordx4 v[124:127], v[100:101], off offset:1024
	v_lshl_add_u64 v[112:113], v[182:183], 0, s[6:7]
	global_load_dwordx4 v[100:103], v[112:113], off offset:-2048
	global_load_dwordx4 v[104:107], v[112:113], off offset:-1024
	global_load_dwordx4 v[108:111], v[112:113], off
	s_nop 0
	global_load_dwordx4 v[112:115], v[112:113], off offset:1024
	ds_read2_b32 v[132:133], v214 offset0:32 offset1:33
	ds_read2_b32 v[134:135], v214 offset0:34 offset1:35
	ds_read2_b32 v[136:137], v214 offset0:36 offset1:37
	ds_read2_b32 v[138:139], v214 offset0:38 offset1:39
	s_cmp_lg_u32 s6, 0x70000
	s_cselect_b32 s92, s20, 0x38000
	s_lshl_b64 s[22:23], s[92:93], 1
	s_add_u32 s6, s6, 0x10000
	s_addc_u32 s7, s7, 0
	s_add_i32 s20, s20, 0x8000
	s_cmp_eq_u32 s6, 0x80000
	s_waitcnt vmcnt(11) lgkmcnt(2)
	v_mfma_f32_16x16x32_bf16 v[140:143], v[218:221], v[8:11], v[132:135]
	s_waitcnt vmcnt(9) lgkmcnt(0)
	v_mfma_f32_16x16x32_bf16 v[144:147], v[226:229], v[8:11], v[136:139]
	v_mfma_f32_16x16x32_bf16 v[234:237], v[222:225], v[12:15], v[140:143]
	s_waitcnt vmcnt(8)
	v_mfma_f32_16x16x32_bf16 v[248:251], v[230:233], v[12:15], v[144:147]
	s_nop 2
	ds_read2_b32 v[140:141], v214 offset0:16 offset1:17
	ds_read2_b32 v[142:143], v214 offset0:18 offset1:19
	ds_read2_b32 v[144:145], v214 offset0:20 offset1:21
	ds_read2_b32 v[146:147], v214 offset0:22 offset1:23
	ds_read2_b32 v[198:199], v214 offset1:1
	ds_read2_b32 v[200:201], v214 offset0:2 offset1:3
	ds_read2_b32 v[244:245], v214 offset0:4 offset1:5
	ds_read2_b32 v[246:247], v214 offset0:6 offset1:7
	v_exp_f32_e32 v186, v234
	s_waitcnt lgkmcnt(6)
	v_mfma_f32_16x16x32_bf16 v[202:205], v[218:221], v[16:19], v[140:143]
	v_exp_f32_e32 v187, v235
	v_exp_f32_e32 v217, v236
	v_cvt_pk_bf16_f32 v186, v186, v187
	s_waitcnt lgkmcnt(2)
	v_mfma_f32_16x16x32_bf16 v[198:201], v[218:221], v[24:27], v[198:201]
	v_mfma_f32_16x16x32_bf16 v[202:205], v[222:225], v[20:23], v[202:205]
	v_mfma_f32_16x16x32_bf16 v[198:201], v[222:225], v[28:31], v[198:201]
	v_exp_f32_e32 v223, v237
	v_exp_f32_e32 v224, v248
	v_exp_f32_e32 v225, v249
	v_mfma_f32_16x16x32_bf16 v[194:197], v[226:229], v[16:19], v[144:147]
	v_and_b32_e32 v222, v32, v186
	v_cvt_pk_bf16_f32 v186, v217, v223
	v_and_b32_e32 v223, v33, v186
	s_waitcnt lgkmcnt(0)
	v_mfma_f32_16x16x32_bf16 v[218:221], v[226:229], v[24:27], v[244:247]
	v_exp_f32_e32 v226, v250
	v_exp_f32_e32 v227, v251
	v_cvt_pk_bf16_f32 v186, v224, v225
	v_mfma_f32_16x16x32_bf16 v[194:197], v[230:233], v[20:23], v[194:197]
	v_and_b32_e32 v224, v34, v186
	v_cvt_pk_bf16_f32 v186, v226, v227
	v_and_b32_e32 v225, v35, v186
	v_exp_f32_e32 v186, v202
	v_exp_f32_e32 v187, v203
	v_exp_f32_e32 v202, v204
	v_exp_f32_e32 v203, v205
	s_nop 0
	v_exp_f32_e32 v204, v194
	v_exp_f32_e32 v205, v195
	v_exp_f32_e32 v217, v196
	v_exp_f32_e32 v197, v197
	v_cvt_pk_bf16_f32 v186, v186, v187
	v_and_b32_e32 v194, v36, v186
	v_cvt_pk_bf16_f32 v186, v202, v203
	v_mfma_f32_16x16x32_bf16 v[218:221], v[230:233], v[28:31], v[218:221]
	v_and_b32_e32 v195, v37, v186
	v_cvt_pk_bf16_f32 v186, v204, v205
	v_and_b32_e32 v196, v38, v186
	v_cvt_pk_bf16_f32 v186, v217, v197
	v_and_b32_e32 v197, v39, v186
	v_exp_f32_e32 v186, v198
	v_exp_f32_e32 v187, v199
	v_exp_f32_e32 v199, v200
	v_exp_f32_e32 v200, v201
	v_exp_f32_e32 v201, v218
	v_exp_f32_e32 v202, v219
	v_exp_f32_e32 v203, v220
	v_exp_f32_e32 v204, v221
	v_cvt_pk_bf16_f32 v186, v186, v187
	v_and_b32_e32 v198, v40, v186
	v_cvt_pk_bf16_f32 v186, v199, v200
	v_and_b32_e32 v199, v41, v186
	v_cvt_pk_bf16_f32 v186, v201, v202
	v_and_b32_e32 v200, v42, v186
	v_cvt_pk_bf16_f32 v186, v203, v204
	v_and_b32_e32 v201, v43, v186
	v_mfma_f32_16x16x32_bf16 v[64:67], v[148:151], v[222:225], v[64:67]
	v_dot2c_f32_bf16 v215, v243, v194
	v_dot2c_f32_bf16 v213, v243, v198
	v_dot2c_f32_bf16 v216, v243, v222
	v_mfma_f32_16x16x32_bf16 v[52:55], v[152:155], v[222:225], v[52:55]
	v_dot2c_f32_bf16 v215, v243, v195
	v_dot2c_f32_bf16 v213, v243, v199
	v_dot2c_f32_bf16 v216, v243, v223
	v_mfma_f32_16x16x32_bf16 v[84:87], v[148:151], v[194:197], v[84:87]
	v_dot2c_f32_bf16 v215, v243, v196
	v_dot2c_f32_bf16 v213, v243, v200
	v_dot2c_f32_bf16 v216, v243, v224
	v_mfma_f32_16x16x32_bf16 v[76:79], v[152:155], v[194:197], v[76:79]
	v_dot2c_f32_bf16 v215, v243, v197
	v_dot2c_f32_bf16 v213, v243, v201
	v_lshl_add_u64 v[186:187], v[178:179], 0, s[22:23]
	v_mfma_f32_16x16x32_bf16 v[96:99], v[148:151], v[198:201], v[96:99]
	v_dot2c_f32_bf16 v216, v243, v225
	v_mfma_f32_16x16x32_bf16 v[92:95], v[152:155], v[198:201], v[92:95]
	ds_read2_b32 v[148:149], v214 offset0:48 offset1:49
	ds_read2_b32 v[150:151], v214 offset0:50 offset1:51
	ds_read2_b32 v[152:153], v214 offset0:52 offset1:53
	ds_read2_b32 v[154:155], v214 offset0:54 offset1:55
	v_add_u32_e32 v214, 0x200, v214
	v_mfma_f32_16x16x32_bf16 v[56:59], v[156:159], v[222:225], v[56:59]
	v_mfma_f32_16x16x32_bf16 v[68:71], v[156:159], v[194:197], v[68:71]
	v_mfma_f32_16x16x32_bf16 v[72:75], v[160:163], v[194:197], v[72:75]
	v_mfma_f32_16x16x32_bf16 v[88:91], v[156:159], v[198:201], v[88:91]
	ds_read_b128 v[156:159], v190 offset:6144
	ds_read_b128 v[194:197], v190 offset:7168
	s_waitcnt vmcnt(7) lgkmcnt(4)
; #define LAS __attribute__((address_space(3)))
; __device__ __forceinline__ float sq4(f32x4 v) { return (v[0] * v[0] + v[1] * v[1]) + (v[2] * v[2] + v[3] * v[3]); }
; __device__ __forceinline__ void attn_phase(LAS unsigned char* lds, const bf16_t* Qb, const bf16_t* Kb, const bf16_t* VT, bf16_t* MIX,
;                                            const float* tblg, const float* ga) {
;     ...
;         ATT_LOADH(kA, vA, 0, 0);
; #pragma unroll 1
;         for (int j = 0; j < 8; ++j) {
;             const int dr = r0 + j - r + 7;
;             const LAS float* trow = tbl + (h * 15 + dr) * 128;
;             ATT_LOADH(kB, vB, j, 1);
;             ATT_HALF(kA, vA, 0);
;             { const int jn = j < 7 ? j + 1 : 7; ATT_LOADH(kA, vA, jn, 0); }
;             ATT_HALF(kB, vB, 1);
;     ...
;         float ssq[4];
; #pragma unroll
;         for (int qt = 0; qt < 4; ++qt) {
;             float lt = l[qt]; lt += __shfl_xor(lt, 16); lt += __shfl_xor(lt, 32);
;             const float inv = __builtin_amdgcn_rcpf(lt); float ss = 0.f;
; #pragma unroll
;             for (int nt = 0; nt < 4; ++nt) { O[qt][nt] = O[qt][nt] * inv; ss += sq4(O[qt][nt]); }
;             ss += __shfl_xor(ss, 16); ss += __shfl_xor(ss, 32);
;             ssq[qt] = ss;
;             if (fq == 0) red[h * 64 + 16 * qt + fr] = ss;
	v_mfma_f32_16x16x32_bf16 v[148:151], v[120:123], v[16:19], v[148:151]
	s_waitcnt vmcnt(5) lgkmcnt(2)
	v_mfma_f32_16x16x32_bf16 v[152:155], v[128:131], v[16:19], v[152:155]
	v_mfma_f32_16x16x32_bf16 v[148:151], v[116:119], v[20:23], v[148:151]
	v_mfma_f32_16x16x32_bf16 v[132:135], v[120:123], v[24:27], v[132:135]
	v_mfma_f32_16x16x32_bf16 v[136:139], v[128:131], v[24:27], v[136:139]
	s_waitcnt lgkmcnt(1)
	v_mfma_f32_16x16x32_bf16 v[120:123], v[120:123], v[156:159], v[140:143]
	v_mfma_f32_16x16x32_bf16 v[128:131], v[128:131], v[156:159], v[144:147]
	s_waitcnt vmcnt(4)
	v_mfma_f32_16x16x32_bf16 v[152:155], v[124:127], v[20:23], v[152:155]
	v_mfma_f32_16x16x32_bf16 v[132:135], v[116:119], v[28:31], v[132:135]
	v_mfma_f32_16x16x32_bf16 v[136:139], v[124:127], v[28:31], v[136:139]
	s_nop 5
	v_exp_f32_e32 v140, v152
	v_exp_f32_e32 v141, v153
	v_exp_f32_e32 v142, v154
	s_waitcnt lgkmcnt(0)
	v_mfma_f32_16x16x32_bf16 v[116:119], v[116:119], v[194:197], v[120:123]
	v_exp_f32_e32 v143, v155
	v_exp_f32_e32 v132, v132
	v_exp_f32_e32 v133, v133
	v_mfma_f32_16x16x32_bf16 v[120:123], v[124:127], v[194:197], v[128:131]
	ds_read_b128 v[124:127], v207 offset:2048
	v_exp_f32_e32 v134, v134
	v_exp_f32_e32 v135, v135
	v_exp_f32_e32 v128, v148
	v_exp_f32_e32 v129, v149
	v_exp_f32_e32 v130, v150
	v_exp_f32_e32 v131, v151
	v_exp_f32_e32 v136, v136
	v_cvt_pk_bf16_f32 v128, v128, v129
	s_waitcnt lgkmcnt(0)
	v_and_b32_e32 v124, v124, v128
	v_cvt_pk_bf16_f32 v128, v130, v131
	v_and_b32_e32 v125, v125, v128
	v_cvt_pk_bf16_f32 v128, v140, v141
	v_and_b32_e32 v126, v126, v128
	v_cvt_pk_bf16_f32 v128, v142, v143
	v_and_b32_e32 v127, v127, v128
	ds_read_b128 v[128:131], v207 offset:4096
	v_exp_f32_e32 v137, v137
	v_exp_f32_e32 v138, v138
	v_exp_f32_e32 v139, v139
	v_cvt_pk_bf16_f32 v132, v132, v133
	s_waitcnt lgkmcnt(0)
	v_and_b32_e32 v128, v128, v132
	v_cvt_pk_bf16_f32 v132, v134, v135
	v_and_b32_e32 v129, v129, v132
	v_cvt_pk_bf16_f32 v132, v136, v137
	v_and_b32_e32 v130, v130, v132
	v_cvt_pk_bf16_f32 v132, v138, v139
	v_and_b32_e32 v131, v131, v132
	v_exp_f32_e32 v132, v116
	v_exp_f32_e32 v133, v117
	v_exp_f32_e32 v134, v118
	v_exp_f32_e32 v135, v119
	v_exp_f32_e32 v120, v120
	v_exp_f32_e32 v121, v121
	ds_read_b128 v[116:119], v207 offset:5120
	v_exp_f32_e32 v122, v122
	v_exp_f32_e32 v123, v123
	v_mfma_f32_16x16x32_bf16 v[80:83], v[160:163], v[198:201], v[80:83]
	v_cvt_pk_bf16_f32 v132, v132, v133
	v_cvt_pk_bf16_f32 v120, v120, v121
	s_waitcnt lgkmcnt(0)
	v_and_b32_e32 v116, v116, v132
	v_cvt_pk_bf16_f32 v132, v134, v135
	v_and_b32_e32 v118, v118, v120
	v_cvt_pk_bf16_f32 v120, v122, v123
	v_and_b32_e32 v117, v117, v132
	v_and_b32_e32 v119, v119, v120
	v_mfma_f32_16x16x32_bf16 v[60:63], v[160:163], v[222:225], v[60:63]
	v_dot2c_f32_bf16 v215, v243, v124
	v_dot2c_f32_bf16 v213, v243, v128
	v_dot2c_f32_bf16 v212, v243, v116
	s_waitcnt vmcnt(3)
	v_mfma_f32_16x16x32_bf16 v[84:87], v[100:103], v[124:127], v[84:87]
	v_dot2c_f32_bf16 v215, v243, v125
	v_dot2c_f32_bf16 v213, v243, v129
	v_dot2c_f32_bf16 v212, v243, v117
	s_waitcnt vmcnt(2)
	v_mfma_f32_16x16x32_bf16 v[76:79], v[104:107], v[124:127], v[76:79]
	v_lshl_add_u64 v[160:161], v[180:181], 0, s[22:23]
	v_dot2c_f32_bf16 v215, v243, v126
	v_dot2c_f32_bf16 v213, v243, v130
	s_waitcnt vmcnt(1)
	v_mfma_f32_16x16x32_bf16 v[68:71], v[108:111], v[124:127], v[68:71]
	v_dot2c_f32_bf16 v212, v243, v118
	v_dot2c_f32_bf16 v215, v243, v127
	v_dot2c_f32_bf16 v213, v243, v131
	s_waitcnt vmcnt(0)
	v_mfma_f32_16x16x32_bf16 v[72:75], v[112:115], v[124:127], v[72:75]
	v_dot2c_f32_bf16 v212, v243, v119
	v_mfma_f32_16x16x32_bf16 v[96:99], v[100:103], v[128:131], v[96:99]
	v_mfma_f32_16x16x32_bf16 v[92:95], v[104:107], v[128:131], v[92:95]
	v_mfma_f32_16x16x32_bf16 v[88:91], v[108:111], v[128:131], v[88:91]
	v_mfma_f32_16x16x32_bf16 v[80:83], v[112:115], v[128:131], v[80:83]
	v_mfma_f32_16x16x32_bf16 v[48:51], v[100:103], v[116:119], v[48:51]
	v_mfma_f32_16x16x32_bf16 v[44:47], v[104:107], v[116:119], v[44:47]
	v_mfma_f32_16x16x32_bf16 v[4:7], v[108:111], v[116:119], v[4:7]
	v_mfma_f32_16x16x32_bf16 v[0:3], v[112:115], v[116:119], v[0:3]
	s_cbranch_scc0 .LBB0_649
	global_load_dwordx4 v[112:115], v[172:173], off
	global_load_dwordx4 v[116:119], v[172:173], off offset:64
	global_load_dwordx4 v[120:123], v[172:173], off offset:128
	global_load_dwordx4 v[124:127], v[172:173], off offset:192
	v_and_b32_e32 v9, 64, v242
	v_xor_b32_e32 v8, 16, v242
	v_add_u32_e32 v9, 64, v9
	v_cmp_lt_i32_e64 s[42:43], v8, v9
	v_xor_b32_e32 v10, 32, v242
	s_nop 0
	v_cndmask_b32_e64 v8, v242, v8, s[42:43]
	v_lshlrev_b32_e32 v108, 2, v8
	ds_bpermute_b32 v8, v108, v216
	v_cmp_lt_i32_e64 s[42:43], v10, v9
	s_waitcnt lgkmcnt(0)
	v_add_f32_e32 v8, v216, v8
	v_cndmask_b32_e64 v9, v242, v10, s[42:43]
	v_lshlrev_b32_e32 v109, 2, v9
	ds_bpermute_b32 v9, v109, v8
	s_waitcnt lgkmcnt(0)
	v_add_f32_e32 v8, v8, v9
	v_rcp_f32_e32 v8, v8
	s_nop 0
	v_pk_mul_f32 v[100:101], v[66:67], v[8:9] op_sel_hi:[1,0]
	v_pk_mul_f32 v[102:103], v[64:65], v[8:9] op_sel_hi:[1,0]
	v_pk_mul_f32 v[64:65], v[54:55], v[8:9] op_sel_hi:[1,0]
	v_pk_mul_f32 v[66:67], v[52:53], v[8:9] op_sel_hi:[1,0]
	v_mul_f32_e32 v9, v103, v103
	v_mul_f32_e32 v10, v101, v101
	v_fmac_f32_e32 v9, v102, v102
	v_fmac_f32_e32 v10, v100, v100
	v_add_f32_e32 v9, v9, v10
	v_mul_f32_e32 v10, v67, v67
	v_mul_f32_e32 v11, v65, v65
	v_fmac_f32_e32 v10, v66, v66
	v_fmac_f32_e32 v11, v64, v64
	v_add_f32_e32 v10, v10, v11
	v_add_f32_e32 v9, v9, v10
	v_pk_mul_f32 v[104:105], v[58:59], v[8:9] op_sel_hi:[1,0]
	v_pk_mul_f32 v[106:107], v[56:57], v[8:9] op_sel_hi:[1,0]
	v_mul_f32_e32 v11, v105, v105
	v_mul_f32_e32 v10, v107, v107
	v_fmac_f32_e32 v10, v106, v106
	v_fmac_f32_e32 v11, v104, v104
	v_add_f32_e32 v10, v10, v11
	v_add_f32_e32 v9, v10, v9
	v_pk_mul_f32 v[56:57], v[62:63], v[8:9] op_sel_hi:[1,0]
	v_pk_mul_f32 v[58:59], v[60:61], v[8:9] op_sel_hi:[1,0]
	v_mul_f32_e32 v10, v57, v57
	v_mul_f32_e32 v8, v59, v59
	v_fmac_f32_e32 v8, v58, v58
	v_fmac_f32_e32 v10, v56, v56
	v_add_f32_e32 v8, v8, v10
	v_add_f32_e32 v8, v8, v9
	ds_bpermute_b32 v9, v108, v8
	s_waitcnt lgkmcnt(0)
	v_add_f32_e32 v8, v8, v9
	ds_bpermute_b32 v9, v109, v8
	s_and_saveexec_b64 s[6:7], vcc
	s_cbranch_execz .LBB0_652
	s_waitcnt lgkmcnt(0)
	v_add_f32_e32 v8, v8, v9
	ds_write_b32 v211, v8 offset:61440
